# v090 + P8->P9 grid barrier replaced by the workgroup barrier (P9 tasks on own q tiles, gridDim==256); placement matched
# baseline (speedup 1.0000x reference)
; #define PG8_LAS __attribute__((address_space(3)))
; #define SEAM(k) do { if (IN(k) && IN((k) + 1)) xcd_barrier(xbar); } while (0)
; __global__ void __launch_bounds__(NT, 2) mk_fwd(Args args) {
;     ...
;         pg8::gemm_phase<pg8::EpiBf16G, pg8::StaticOrder, true, true>((PG8_LAS unsigned char*)lds, g, S, E);
;     }
;     SEAM(8);
.LBB0_811:
	s_or_b64 exec, exec, s[2:3]
	s_waitcnt lgkmcnt(0)
	s_barrier
	s_nop 0
	s_nop 0
	s_nop 0
	s_nop 0
	s_nop 0
	s_nop 0
	s_nop 0
	s_nop 0
	s_nop 0
	s_nop 0
	s_nop 0
	s_nop 0
	s_nop 0
	s_nop 0
	s_nop 0
	s_nop 0
	s_nop 0
	s_nop 0
	s_nop 0
	s_nop 0
	s_nop 0
	s_nop 0
	s_nop 0
	s_nop 0
	s_nop 0
	s_nop 0
	s_nop 0

; __device__ __forceinline__ float bf_lo(unsigned u) { return __uint_as_float(u << 16); }
; __device__ __forceinline__ float bf_hi(unsigned u) { return __uint_as_float(u & 0xffff0000u); }
; #define SEAM(k) do { if (IN(k) && IN((k) + 1)) xcd_barrier(xbar); } while (0)
; __global__ void __launch_bounds__(NT, 2) mk_fwd(Args args) {
;     ...
;     SEAM(9);
;     if (IN(10)) {
;         const float* fg = args.in[28];
;         for (int tok = gw; tok < MTOK; tok += NGW) {
;             const int b = tok >> 11;
;             f32x2 hf2[16];
; #pragma unroll
;             for (int j = 0; j < 4; ++j) { const u32x4 a = *(const u32x4*)(HB + (size_t)tok * DM + lane * 32 + j * 8);
; #pragma unroll
;                 for (int q = 0; q < 4; ++q) hf2[j * 4 + q] = (f32x2){bf_lo(a[q]), bf_hi(a[q])}; }
;             const int e0 = EIDX[(size_t)tok * 128 + lane], e1 = EIDX[(size_t)tok * 128 + 64 + lane];
;             const float g0 = GATE[(size_t)tok * 128 + lane], g1 = GATE[(size_t)tok * 128 + 64 + lane];
;             const bool hi32 = (lane & 32) != 0, hi16 = (lane & 16) != 0; const int l3 = (lane & 3) << 4;
.LBB0_881:
	s_or_b64 exec, exec, s[8:9]
	s_waitcnt vmcnt(0)
.LBB0_882:
	s_or_b64 exec, exec, s[2:3]
	s_waitcnt lgkmcnt(0)
	s_barrier
	s_nop 0
	s_nop 0
	s_nop 0
	s_nop 0
	s_nop 0
	s_nop 0
	s_nop 0
	s_nop 0
	s_nop 0
	s_nop 0
	s_nop 0
	s_nop 0
	s_nop 0
.LBB0_883:
	s_cmp_lt_i32 s94, 11
	s_cselect_b64 s[2:3], -1, 0
	s_and_b64 s[0:1], s[2:3], s[0:1]
	s_and_b64 s[0:1], s[0:1], s[86:87]
	s_andn2_b64 vcc, exec, s[0:1]
	s_cbranch_vccnz .LBB0_913
	s_waitcnt vmcnt(0)
	v_mbcnt_hi_u32_b32 v3, -1, v169
	v_and_b32_e32 v5, 64, v3
	v_xor_b32_e32 v4, 32, v3
	v_add_u32_e32 v6, 64, v5
	v_cmp_lt_i32_e32 vcc, v4, v6
	v_mov_b32_e32 v137, 0
	v_and_b32_e32 v0, 32, v168
	v_cndmask_b32_e32 v4, v3, v4, vcc
	v_cmp_eq_u32_e64 s[0:1], 0, v0
	v_and_b32_e32 v0, 16, v168
	v_mov_b32_e32 v131, v137
	v_lshlrev_b32_e32 v129, 2, v4
	v_xor_b32_e32 v4, 16, v3
	v_cmp_eq_u32_e64 s[2:3], 0, v0
	v_lshlrev_b32_e32 v2, 4, v168
	v_lshl_add_u64 v[0:1], s[92:93], 0, v[130:131]
	s_mov_b64 s[4:5], 0x2a00000
	v_cmp_lt_i32_e32 vcc, v4, v6
	s_add_u32 s6, s92, 0x6a00000
	v_lshl_add_u64 v[96:97], s[80:81], 0, v[136:137]
	v_lshl_add_u64 v[98:99], v[0:1], 0, s[4:5]
	v_cndmask_b32_e32 v3, v3, v4, vcc
	v_and_or_b32 v2, v2, 48, v5
	s_mov_b64 s[4:5], 0x4a00000
	v_lshlrev_b32_e32 v136, 7, v128
	v_and_b32_e32 v148, 60, v128
	s_addc_u32 s7, s93, 0
	v_lshlrev_b32_e32 v146, 2, v3
	v_lshlrev_b32_e32 v147, 2, v2
	v_lshl_add_u64 v[100:101], v[0:1], 0, s[4:5]
	v_lshl_add_u64 v[102:103], s[90:91], 0, v[136:137]
	v_lshl_add_u64 v[104:105], s[88:89], 0, v[136:137]
	v_add_u32_e32 v149, -12, v148
	v_add_u32_e32 v150, -8, v148
	v_add_u32_e32 v151, -4, v148
	s_mov_b32 s11, 0x378e98ab
	s_mov_b32 s13, 0x3b7cd369
	s_mov_b32 s15, 0xbcc618b2
	s_mov_b32 s17, 0x3dda74e4
	s_mov_b32 s19, 0x3f228afd
	s_mov_b32 s21, 0x3e03c728
	s_mov_b32 s23, 0xbfb8aa3b
	s_mov_b32 s25, 0x42ce8ed0
	s_mov_b32 s26, 0xc2b17218
	v_mov_b32_e32 v152, 0x3ba10414
	s_brev_b32 s27, -2
	v_lshlrev_b32_e32 v136, 2, v138
	s_mov_b64 s[8:9], 0xa000
	s_mov_b32 s28, 0xa000
	v_mov_b32_e32 v153, 0x358637bd
	s_mov_b32 s29, 0x800000
	v_mov_b32_e32 v154, 0xb9c68948
	v_mov_b32_e32 v155, 0x7f800000
	s_mov_b32 s50, 0x55555555
	s_mov_b32 s51, 0x55555555
	s_mov_b32 s52, 0x33333333
	s_mov_b32 s53, 0x33333333
	s_mov_b32 s54, 0xf0f0f0f
	s_mov_b32 s55, 0xf0f0f0f
	s_mov_b32 s56, 0xff00ff
	s_mov_b32 s57, 0xff00ff
	s_mov_b32 s58, 0xffff
	s_mov_b32 s59, 0xffff
	s_mov_b32 s60, -1
	s_mov_b32 s61, 0
	global_load_dwordx4 v[186:189], v[104:105], off
	global_load_dwordx4 v[190:193], v[104:105], off offset:16
	global_load_dwordx4 v[194:197], v[104:105], off offset:32
	global_load_dwordx4 v[198:201], v[104:105], off offset:48
	global_load_dwordx4 v[202:205], v[104:105], off offset:64
	global_load_dwordx4 v[206:209], v[104:105], off offset:80
	global_load_dwordx4 v[210:213], v[104:105], off offset:96
	global_load_dwordx4 v[214:217], v[104:105], off offset:112
	s_waitcnt vmcnt(0)
	s_branch .LBB0_886
